# sparse attention far stage hand-written: select bits via v_add_co carry, in-place -inf masking (no second select), permlane32 cross-half max, in-place bf16 pack
# speedup vs baseline: 1.0183x; 1.0109x over previous
; DI f32x16 mfma32(bf16x8 a, bf16x8 b, f32x16 c) { return __builtin_amdgcn_mfma_f32_32x32x16_bf16(a, b, c, 0, 0, 0); }
; DI void sparse_job(const Params& p, int layer, int b, int head, int qb, unsigned char* smem) {
;     ...
;       const float off = cbias - m;
;       float la = 0.f, lb = 0.f;
; #pragma unroll
;       for (int i = 0; i < 16; ++i) {
;         const float pa = (sa & (1u << i)) ? __builtin_amdgcn_exp2f(S0[i] * csc + off) : 0.f;
;         const float pb = (sb2 & (1u << i)) ? __builtin_amdgcn_exp2f(S1[i] * csc + off) : 0.f;
;         la += pa; lb += pb; S0[i] = pa; S1[i] = pb;
;       }
;       l += la + lb;
;       const bf16x8 p0 = pack8(S0, 0), p1 = pack8(S0, 1), p2 = pack8(S1, 0), p3 = pack8(S1, 1);
; #pragma unroll
;       for (int d = 0; d < 2; ++d) {
;         const unsigned char* vr = sb + 9216 + (d * 32 + lq) * 144 + 16 * h;
;         bf16x8 v0 = *(const bf16x8*)(vr), v1 = *(const bf16x8*)(vr + 32), v2 = *(const bf16x8*)(vr + 64), v3 = *(const bf16x8*)(vr + 96);
;         O[d] = mfma32(v0, p0, O[d]);
;         O[d] = mfma32(v1, p1, O[d]);
;         O[d] = mfma32(v2, p2, O[d]);
;         O[d] = mfma32(v3, p3, O[d]);
;       }
.LBB0_322:
	v_sub_f32_e32 v0, v0, v120
	ds_read_b128 v[154:157], v153 offset:9216
	ds_read_b128 v[158:161], v153 offset:9248
	v_fmamk_f32 v50, v50, 0x3e38aa3b, v0
	v_exp_f32_e32 v50, v50
	v_fmamk_f32 v51, v51, 0x3e38aa3b, v0
	v_exp_f32_e32 v51, v51
	v_fmamk_f32 v52, v52, 0x3e38aa3b, v0
	v_exp_f32_e32 v52, v52
	v_add_f32_e32 v120, v50, v51
	v_cvt_pk_bf16_f32 v50, v50, v51
	v_fmamk_f32 v53, v53, 0x3e38aa3b, v0
	v_exp_f32_e32 v53, v53
	v_add_f32_e32 v120, v120, v52
	v_fmamk_f32 v54, v54, 0x3e38aa3b, v0
	v_exp_f32_e32 v54, v54
	v_add_f32_e32 v120, v120, v53
	v_cvt_pk_bf16_f32 v51, v52, v53
	v_fmamk_f32 v55, v55, 0x3e38aa3b, v0
	v_exp_f32_e32 v55, v55
	v_add_f32_e32 v120, v120, v54
	v_fmamk_f32 v56, v56, 0x3e38aa3b, v0
	v_exp_f32_e32 v56, v56
	v_add_f32_e32 v120, v120, v55
	v_cvt_pk_bf16_f32 v52, v54, v55
	v_fmamk_f32 v57, v57, 0x3e38aa3b, v0
	v_exp_f32_e32 v57, v57
	v_add_f32_e32 v120, v120, v56
	v_fmamk_f32 v58, v58, 0x3e38aa3b, v0
	v_exp_f32_e32 v58, v58
	v_add_f32_e32 v120, v120, v57
	v_cvt_pk_bf16_f32 v53, v56, v57
	v_fmamk_f32 v59, v59, 0x3e38aa3b, v0
	v_exp_f32_e32 v59, v59
	v_add_f32_e32 v120, v120, v58
	v_fmamk_f32 v60, v60, 0x3e38aa3b, v0
	v_exp_f32_e32 v60, v60
	v_add_f32_e32 v120, v120, v59
	v_cvt_pk_bf16_f32 v54, v58, v59
	v_fmamk_f32 v61, v61, 0x3e38aa3b, v0
	v_exp_f32_e32 v61, v61
	v_add_f32_e32 v120, v120, v60
	v_fmamk_f32 v62, v62, 0x3e38aa3b, v0
	v_exp_f32_e32 v62, v62
	v_add_f32_e32 v120, v120, v61
	v_cvt_pk_bf16_f32 v55, v60, v61
	v_fmamk_f32 v63, v63, 0x3e38aa3b, v0
	v_exp_f32_e32 v63, v63
	v_add_f32_e32 v120, v120, v62
	v_fmamk_f32 v64, v64, 0x3e38aa3b, v0
	v_exp_f32_e32 v64, v64
	v_add_f32_e32 v120, v120, v63
	v_cvt_pk_bf16_f32 v56, v62, v63
	v_fmamk_f32 v65, v65, 0x3e38aa3b, v0
	v_exp_f32_e32 v65, v65
	v_add_f32_e32 v120, v120, v64
	v_add_f32_e32 v120, v120, v65
	v_cvt_pk_bf16_f32 v57, v64, v65
	ds_read_b128 v[58:61], v153 offset:13824
	ds_read_b128 v[62:65], v153 offset:13856
	s_waitcnt lgkmcnt(3)
	v_mfma_f32_32x32x16_bf16 v[2:17], v[154:157], v[50:53], v[2:17]
	v_fmamk_f32 v34, v34, 0x3e38aa3b, v0
	v_exp_f32_e32 v34, v34
	v_fmamk_f32 v35, v35, 0x3e38aa3b, v0
	v_exp_f32_e32 v35, v35
	v_fmamk_f32 v36, v36, 0x3e38aa3b, v0
	v_exp_f32_e32 v36, v36
	v_add_f32_e32 v121, v34, v35
	v_cvt_pk_bf16_f32 v34, v34, v35
	v_fmamk_f32 v37, v37, 0x3e38aa3b, v0
	v_exp_f32_e32 v37, v37
	v_add_f32_e32 v121, v121, v36
	s_waitcnt lgkmcnt(1)
	v_mfma_f32_32x32x16_bf16 v[18:33], v[58:61], v[50:53], v[18:33]
	v_fmamk_f32 v38, v38, 0x3e38aa3b, v0
	v_exp_f32_e32 v38, v38
	v_add_f32_e32 v121, v121, v37
	v_cvt_pk_bf16_f32 v35, v36, v37
	v_fmamk_f32 v39, v39, 0x3e38aa3b, v0
	v_exp_f32_e32 v39, v39
	v_add_f32_e32 v121, v121, v38
	v_fmamk_f32 v40, v40, 0x3e38aa3b, v0
	v_exp_f32_e32 v40, v40
	v_add_f32_e32 v121, v121, v39
	v_cvt_pk_bf16_f32 v36, v38, v39
	v_fmamk_f32 v41, v41, 0x3e38aa3b, v0
	v_exp_f32_e32 v41, v41
	v_add_f32_e32 v121, v121, v40
	s_waitcnt lgkmcnt(1)
	v_mfma_f32_32x32x16_bf16 v[2:17], v[158:161], v[54:57], v[2:17]
	v_fmamk_f32 v42, v42, 0x3e38aa3b, v0
	v_exp_f32_e32 v42, v42
	v_add_f32_e32 v121, v121, v41
	v_cvt_pk_bf16_f32 v37, v40, v41
	v_fmamk_f32 v43, v43, 0x3e38aa3b, v0
	v_exp_f32_e32 v43, v43
	v_add_f32_e32 v121, v121, v42
	v_fmamk_f32 v44, v44, 0x3e38aa3b, v0
	v_exp_f32_e32 v44, v44
	v_add_f32_e32 v121, v121, v43
	v_cvt_pk_bf16_f32 v38, v42, v43
	v_fmamk_f32 v45, v45, 0x3e38aa3b, v0
	v_exp_f32_e32 v45, v45
	v_add_f32_e32 v121, v121, v44
	s_waitcnt lgkmcnt(0)
	v_mfma_f32_32x32x16_bf16 v[18:33], v[62:65], v[54:57], v[18:33]
	v_fmamk_f32 v46, v46, 0x3e38aa3b, v0
	v_exp_f32_e32 v46, v46
	v_add_f32_e32 v121, v121, v45
	v_cvt_pk_bf16_f32 v39, v44, v45
	v_fmamk_f32 v47, v47, 0x3e38aa3b, v0
	v_exp_f32_e32 v47, v47
	v_add_f32_e32 v121, v121, v46
	v_fmamk_f32 v48, v48, 0x3e38aa3b, v0
	v_exp_f32_e32 v48, v48
	v_add_f32_e32 v121, v121, v47
	v_cvt_pk_bf16_f32 v40, v46, v47
	v_fmamk_f32 v49, v49, 0x3e38aa3b, v0
	v_exp_f32_e32 v49, v49
	v_add_f32_e32 v121, v121, v48
	v_add_f32_e32 v121, v121, v49
	v_cvt_pk_bf16_f32 v41, v48, v49
	ds_read_b128 v[154:157], v153 offset:9280
	ds_read_b128 v[58:61], v153 offset:13888
	ds_read_b128 v[158:161], v153 offset:9312
	ds_read_b128 v[62:65], v153 offset:13920
	v_add_f32_e32 v121, v121, v120
	s_nop 0
	v_add_f32_e32 v150, v150, v121
	s_waitcnt lgkmcnt(3)
	v_mfma_f32_32x32x16_bf16 v[2:17], v[154:157], v[34:37], v[2:17]
	s_waitcnt lgkmcnt(2)
	v_mfma_f32_32x32x16_bf16 v[18:33], v[58:61], v[34:37], v[18:33]
	s_waitcnt lgkmcnt(1)
	v_mfma_f32_32x32x16_bf16 v[2:17], v[158:161], v[38:41], v[2:17]
	s_waitcnt lgkmcnt(0)
	v_mfma_f32_32x32x16_bf16 v[18:33], v[62:65], v[38:41], v[18:33]

; DI f32x16 mfma32(bf16x8 a, bf16x8 b, f32x16 c) { return __builtin_amdgcn_mfma_f32_32x32x16_bf16(a, b, c, 0, 0, 0); }
; DI void sparse_job(const Params& p, int layer, int b, int head, int qb, unsigned char* smem) {
;     ...
;       f32x16 S0 = zero16(), S1 = zero16();
; #pragma unroll
;       for (int s = 0; s < 4; ++s) {
;         bf16x8 k0 = *(const bf16x8*)(sb + lq * 144 + (16 * s + 8 * h) * 2);
;         bf16x8 k1 = *(const bf16x8*)(sb + (32 + lq) * 144 + (16 * s + 8 * h) * 2);
;         S0 = mfma32(k0, qf[s], S0);
;         S1 = mfma32(k1, qf[s], S1);
;       }
;       const u32 sa = ((mcur[0] >> (8 * h)) & 0xffu) | (((mcur[0] >> (16 + 8 * h)) & 0xffu) << 8);
;       const u32 sb2 = ((mcur[1] >> (8 * h)) & 0xffu) | (((mcur[1] >> (16 + 8 * h)) & 0xffu) << 8);
;       float mx = -1e30f;
; #pragma unroll
;       for (int i = 0; i < 16; ++i) {
;         mx = fmaxf(mx, (sa & (1u << i)) ? S0[i] : -1e30f);
;         mx = fmaxf(mx, (sb2 & (1u << i)) ? S1[i] : -1e30f);
;       }
;       mx = fmaxf(mx, __shfl_xor(mx, 32));
;       const float mn = mx > -1e29f ? fmaxf(m, mx * csc + cbias) : m;
;       if (__any(mn > m + 8.f)) {
;         const float a = __builtin_amdgcn_exp2f(m - mn);
;         l *= a; O[0] *= a; O[1] *= a;
;         m = mn;
;       }
;       const float off = cbias - m;
.LBB0_351:
	s_andn2_saveexec_b64 s[28:29], s[66:67]
	s_cbranch_execz .LBB0_323
	v_add3_u32 v153, v152, v135, v100
	ds_read_b32 v0, v133
	ds_read_b128 v[34:37], v153 offset:4608
	ds_read_b128 v[38:41], v153
	ds_read_b128 v[154:157], v153 offset:32
	ds_read_b128 v[158:161], v153 offset:4640
	s_waitcnt lgkmcnt(2)
	v_mfma_f32_32x32x16_bf16 v[50:65], v[38:41], v[66:69], 0
	v_mfma_f32_32x32x16_bf16 v[34:49], v[34:37], v[66:69], 0
	s_waitcnt lgkmcnt(1)
	v_mfma_f32_32x32x16_bf16 v[50:65], v[154:157], v[70:73], v[50:65]
	s_waitcnt lgkmcnt(0)
	v_mfma_f32_32x32x16_bf16 v[34:49], v[158:161], v[70:73], v[34:49]
	ds_read_b128 v[154:157], v153 offset:64
	ds_read_b128 v[158:161], v153 offset:4672
	s_waitcnt lgkmcnt(1)
	v_mfma_f32_32x32x16_bf16 v[50:65], v[154:157], v[74:77], v[50:65]
	s_waitcnt lgkmcnt(0)
	v_mfma_f32_32x32x16_bf16 v[34:49], v[158:161], v[74:77], v[34:49]
	ds_read_b128 v[154:157], v153 offset:96
	ds_read_b128 v[158:161], v153 offset:4704
	s_waitcnt lgkmcnt(1)
	v_mfma_f32_32x32x16_bf16 v[50:65], v[154:157], v[78:81], v[50:65]
	s_waitcnt lgkmcnt(0)
	v_mfma_f32_32x32x16_bf16 v[34:49], v[158:161], v[78:81], v[34:49]
	v_bfe_u32 v158, v120, v116, 8
	v_bfe_u32 v159, v120, v134, 8
	v_bfe_u32 v160, v121, v116, 8
	v_bfe_u32 v161, v121, v134, 8
	v_lshlrev_b32_e32 v158, 16, v158
	v_lshlrev_b32_e32 v160, 16, v160
	v_lshl_or_b32 v156, v159, 24, v158
	v_lshl_or_b32 v157, v161, 24, v160
	v_mov_b32_e32 v161, 0xff800000
	v_add_co_u32_e64 v156, s[2:3], v156, v156
	v_add_co_u32_e64 v157, s[4:5], v157, v157
	v_add_co_u32_e64 v156, s[6:7], v156, v156
	v_add_co_u32_e64 v157, s[8:9], v157, v157
	v_cndmask_b32_e64 v65, v161, v65, s[2:3]
	v_cndmask_b32_e64 v49, v161, v49, s[4:5]
	v_cndmask_b32_e64 v64, v161, v64, s[6:7]
	v_cndmask_b32_e64 v48, v161, v48, s[8:9]
	v_add_co_u32_e64 v156, s[2:3], v156, v156
	v_add_co_u32_e64 v157, s[4:5], v157, v157
	v_add_co_u32_e64 v156, s[6:7], v156, v156
	v_add_co_u32_e64 v157, s[8:9], v157, v157
	v_cndmask_b32_e64 v63, v161, v63, s[2:3]
	v_cndmask_b32_e64 v47, v161, v47, s[4:5]
	v_cndmask_b32_e64 v62, v161, v62, s[6:7]
	v_cndmask_b32_e64 v46, v161, v46, s[8:9]
	v_add_co_u32_e64 v156, s[2:3], v156, v156
	v_add_co_u32_e64 v157, s[4:5], v157, v157
	v_add_co_u32_e64 v156, s[6:7], v156, v156
	v_add_co_u32_e64 v157, s[8:9], v157, v157
	v_cndmask_b32_e64 v61, v161, v61, s[2:3]
	v_cndmask_b32_e64 v45, v161, v45, s[4:5]
	v_cndmask_b32_e64 v60, v161, v60, s[6:7]
	v_cndmask_b32_e64 v44, v161, v44, s[8:9]
	v_add_co_u32_e64 v156, s[2:3], v156, v156
	v_add_co_u32_e64 v157, s[4:5], v157, v157
	v_add_co_u32_e64 v156, s[6:7], v156, v156
	v_add_co_u32_e64 v157, s[8:9], v157, v157
	v_cndmask_b32_e64 v59, v161, v59, s[2:3]
	v_cndmask_b32_e64 v43, v161, v43, s[4:5]
	v_cndmask_b32_e64 v58, v161, v58, s[6:7]
	v_cndmask_b32_e64 v42, v161, v42, s[8:9]
	v_add_co_u32_e64 v156, s[2:3], v156, v156
	v_add_co_u32_e64 v157, s[4:5], v157, v157
	v_add_co_u32_e64 v156, s[6:7], v156, v156
	v_add_co_u32_e64 v157, s[8:9], v157, v157
	v_cndmask_b32_e64 v57, v161, v57, s[2:3]
	v_cndmask_b32_e64 v41, v161, v41, s[4:5]
	v_cndmask_b32_e64 v56, v161, v56, s[6:7]
	v_cndmask_b32_e64 v40, v161, v40, s[8:9]
	v_add_co_u32_e64 v156, s[2:3], v156, v156
	v_add_co_u32_e64 v157, s[4:5], v157, v157
	v_add_co_u32_e64 v156, s[6:7], v156, v156
	v_add_co_u32_e64 v157, s[8:9], v157, v157
	v_cndmask_b32_e64 v55, v161, v55, s[2:3]
	v_cndmask_b32_e64 v39, v161, v39, s[4:5]
	v_cndmask_b32_e64 v54, v161, v54, s[6:7]
	v_cndmask_b32_e64 v38, v161, v38, s[8:9]
	v_add_co_u32_e64 v156, s[2:3], v156, v156
	v_add_co_u32_e64 v157, s[4:5], v157, v157
	v_add_co_u32_e64 v156, s[6:7], v156, v156
	v_add_co_u32_e64 v157, s[8:9], v157, v157
	v_cndmask_b32_e64 v53, v161, v53, s[2:3]
	v_cndmask_b32_e64 v37, v161, v37, s[4:5]
	v_cndmask_b32_e64 v52, v161, v52, s[6:7]
	v_cndmask_b32_e64 v36, v161, v36, s[8:9]
	v_add_co_u32_e64 v156, s[2:3], v156, v156
	v_add_co_u32_e64 v157, s[4:5], v157, v157
	v_add_co_u32_e64 v156, s[6:7], v156, v156
	v_add_co_u32_e64 v157, s[8:9], v157, v157
	v_cndmask_b32_e64 v51, v161, v51, s[2:3]
	v_cndmask_b32_e64 v35, v161, v35, s[4:5]
	v_cndmask_b32_e64 v50, v161, v50, s[6:7]
	v_cndmask_b32_e64 v34, v161, v34, s[8:9]
	v_max3_f32 v158, v50, v51, v52
	v_max3_f32 v158, v158, v53, v54
	v_max3_f32 v158, v158, v55, v56
	v_max3_f32 v158, v158, v57, v58
	v_max3_f32 v158, v158, v59, v60
	v_max3_f32 v158, v158, v61, v62
	v_max3_f32 v158, v158, v63, v64
	v_max_f32_e32 v158, v158, v65
	v_max3_f32 v158, v158, v34, v35
	v_max3_f32 v158, v158, v36, v37
	v_max3_f32 v158, v158, v38, v39
	v_max3_f32 v158, v158, v40, v41
	v_max3_f32 v158, v158, v42, v43
	v_max3_f32 v158, v158, v44, v45
	v_max3_f32 v158, v158, v46, v47
	v_max3_f32 v158, v158, v48, v49
	v_mov_b32_e32 v159, v158
	s_nop 1
	v_permlane32_swap_b32_e32 v159, v158
	v_add_f32_e32 v121, 0x41000000, v151
	v_max_f32_e32 v158, v158, v159
	v_cmp_lt_f32_e32 vcc, s25, v158
	v_fmamk_f32 v158, v158, 0x3e38aa3b, v0
	v_max_f32_e32 v158, v151, v158
	s_nop 0
	v_cndmask_b32_e32 v120, v151, v158, vcc
	v_cmp_gt_f32_e32 vcc, v120, v121
	s_cbranch_vccnz .LBB0_321
	v_mov_b32_e32 v120, v151
	s_branch .LBB0_322
